# out-projection (layer 0) epilogue: non-temporal hint on the residual-input loads (read once)
# speedup vs baseline: 1.0048x; 1.0048x over previous
; DI int grow_of(int lrow, int seg) { return (lrow / SEG) * S + seg * SEG + (lrow % SEG); }
;     DI void operator()(const f32x4 (&acc)[2][2][4][2], const Unit& u, int wr, int wc, int fr, int fq) const {
;         const int b = u.pm / TPB;
;         const int lrow0 = u.pm * BM + wr * 64 + fr;
;         const int col0 = u.pn * BM + wc * 32 + 8 * fq;
;         f32x4 gv[2][2];
; #pragma unroll
;         for (int bj = 0; bj < 2; ++bj)
; #pragma unroll
;             for (int n = 0; n < 2; ++n) gv[bj][n] = *(const f32x4*)(gate + b * 3072 + col0 + bj * HALF + 4 * n);
; #pragma unroll
;         for (int ai = 0; ai < 2; ++ai)
; #pragma unroll
;             for (int m = 0; m < 4; ++m) {
;                 const size_t off = (size_t)grow_of(lrow0 + ai * HALF + m * 16, seg) * D + col0;
; #pragma unroll
;                 for (int bj = 0; bj < 2; ++bj)
; #pragma unroll
;                     for (int n = 0; n < 2; ++n) {
;                         const f32x4 xo = *(const f32x4*)(xin + off + bj * HALF + 4 * n);
;                         *(f32x4*)(xout + off + bj * HALF + 4 * n) = xo + gv[bj][n] * acc[ai][bj][m][n];
;                     }
;             }
;     }
.LBB0_794:
	v_lshl_add_u32 v163, s30, 8, v158
	v_ashrrev_i32_e32 v130, 31, v163
	v_lshrrev_b32_e32 v180, 20, v130
	s_ashr_i32 s6, s30, 31
	v_add_u32_e32 v130, v163, v180
	s_lshr_b32 s6, s6, 28
	v_ashrrev_i32_e32 v130, 12, v130
	s_add_i32 s6, s30, s6
	v_lshlrev_b32_e32 v131, 13, v130
	v_mul_i32_i24_e32 v130, 0x1000, v130
	s_lshr_b32 s6, s6, 4
	v_sub_u32_e32 v130, v163, v130
	s_mul_i32 s18, s6, 0xc00
	v_add3_u32 v130, v130, s84, v131
	v_lshl_or_b32 v156, s31, 8, v160
	s_ashr_i32 s19, s18, 31
	v_ashrrev_i32_e32 v131, 31, v130
	s_lshl_b64 s[18:19], s[18:19], 2
	v_ashrrev_i32_e32 v157, 31, v156
	v_lshlrev_b64 v[130:131], 10, v[130:131]
	s_add_u32 s18, s33, s18
	v_readlane_b32 s6, v250, 40
	v_lshl_add_u64 v[130:131], v[130:131], 0, v[156:157]
	s_addc_u32 s19, s6, s19
	v_lshlrev_b64 v[172:173], 2, v[130:131]
	v_lshl_add_u64 v[134:135], v[156:157], 2, s[18:19]
	global_load_dwordx4 v[142:145], v[134:135], off
	global_load_dwordx4 v[138:141], v[134:135], off offset:16
	global_load_dwordx4 v[130:133], v[134:135], off offset:528
	s_nop 0
	global_load_dwordx4 v[134:137], v[134:135], off offset:512
	s_and_b64 vcc, exec, s[42:43]
	s_mov_b64 s[42:43], -1
	s_mov_b32 s39, 0x3fb8aa3b
	v_add_u32_e32 v173, 0x10000, v172
	v_add_u32_e32 v174, 0x20000, v172
	v_add_u32_e32 v175, 0x30000, v172
	v_add_u32_e32 v176, 0x80000, v172
	v_add_u32_e32 v177, 0x90000, v172
	v_add_u32_e32 v178, 0xa0000, v172
	v_add_u32_e32 v179, 0xb0000, v172
	global_load_dwordx4 v[180:183], v172, s[4:5] nt
	global_load_dwordx4 v[184:187], v172, s[4:5] offset:16 nt
	global_load_dwordx4 v[188:191], v172, s[4:5] offset:512 nt
	global_load_dwordx4 v[192:195], v172, s[4:5] offset:528 nt
	global_load_dwordx4 v[218:221], v173, s[4:5] nt
	global_load_dwordx4 v[222:225], v173, s[4:5] offset:16 nt
	global_load_dwordx4 v[226:229], v173, s[4:5] offset:512 nt
	global_load_dwordx4 v[230:233], v173, s[4:5] offset:528 nt
	global_load_dwordx4 v[234:237], v174, s[4:5] nt
	global_load_dwordx4 v[238:241], v174, s[4:5] offset:16 nt
	global_load_dwordx4 v[242:245], v174, s[4:5] offset:512 nt
	global_load_dwordx4 v[246:249], v174, s[4:5] offset:528 nt
	s_waitcnt vmcnt(8)
	v_pk_fma_f32 v[180:181], v[126:127], v[142:143], v[180:181]
	v_pk_fma_f32 v[182:183], v[128:129], v[144:145], v[182:183]
	v_pk_fma_f32 v[184:185], v[122:123], v[138:139], v[184:185]
	v_pk_fma_f32 v[186:187], v[124:125], v[140:141], v[186:187]
	v_pk_fma_f32 v[188:189], v[118:119], v[134:135], v[188:189]
	v_pk_fma_f32 v[190:191], v[120:121], v[136:137], v[190:191]
	v_pk_fma_f32 v[192:193], v[106:107], v[130:131], v[192:193]
	v_pk_fma_f32 v[194:195], v[108:109], v[132:133], v[194:195]
	global_store_dwordx4 v172, v[180:183], s[74:75]
	global_store_dwordx4 v172, v[184:187], s[74:75] offset:16
	global_store_dwordx4 v172, v[188:191], s[74:75] offset:512
	global_store_dwordx4 v172, v[192:195], s[74:75] offset:528
	s_nop 1
	global_load_dwordx4 v[180:183], v175, s[4:5] nt
	global_load_dwordx4 v[184:187], v175, s[4:5] offset:16 nt
	global_load_dwordx4 v[188:191], v175, s[4:5] offset:512 nt
	global_load_dwordx4 v[192:195], v175, s[4:5] offset:528 nt
	s_waitcnt vmcnt(12)
	v_pk_fma_f32 v[218:219], v[114:115], v[142:143], v[218:219]
	v_pk_fma_f32 v[220:221], v[116:117], v[144:145], v[220:221]
	v_pk_fma_f32 v[222:223], v[110:111], v[138:139], v[222:223]
	v_pk_fma_f32 v[224:225], v[112:113], v[140:141], v[224:225]
	v_pk_fma_f32 v[226:227], v[102:103], v[134:135], v[226:227]
	v_pk_fma_f32 v[228:229], v[104:105], v[136:137], v[228:229]
	v_pk_fma_f32 v[230:231], v[90:91], v[130:131], v[230:231]
	v_pk_fma_f32 v[232:233], v[92:93], v[132:133], v[232:233]
	global_store_dwordx4 v173, v[218:221], s[74:75]
	global_store_dwordx4 v173, v[222:225], s[74:75] offset:16
	global_store_dwordx4 v173, v[226:229], s[74:75] offset:512
	global_store_dwordx4 v173, v[230:233], s[74:75] offset:528
	s_nop 1
	global_load_dwordx4 v[218:221], v176, s[4:5] nt
	global_load_dwordx4 v[222:225], v176, s[4:5] offset:16 nt
	global_load_dwordx4 v[226:229], v176, s[4:5] offset:512 nt
	global_load_dwordx4 v[230:233], v176, s[4:5] offset:528 nt
	s_waitcnt vmcnt(16)
	v_pk_fma_f32 v[234:235], v[98:99], v[142:143], v[234:235]
	v_pk_fma_f32 v[236:237], v[100:101], v[144:145], v[236:237]
	v_pk_fma_f32 v[238:239], v[94:95], v[138:139], v[238:239]
	v_pk_fma_f32 v[240:241], v[96:97], v[140:141], v[240:241]
	v_pk_fma_f32 v[242:243], v[86:87], v[134:135], v[242:243]
	v_pk_fma_f32 v[244:245], v[88:89], v[136:137], v[244:245]
	v_pk_fma_f32 v[246:247], v[74:75], v[130:131], v[246:247]
	v_pk_fma_f32 v[248:249], v[76:77], v[132:133], v[248:249]
	global_store_dwordx4 v174, v[234:237], s[74:75]
	global_store_dwordx4 v174, v[238:241], s[74:75] offset:16
	global_store_dwordx4 v174, v[242:245], s[74:75] offset:512
	global_store_dwordx4 v174, v[246:249], s[74:75] offset:528
	s_nop 1
	global_load_dwordx4 v[234:237], v177, s[4:5] nt
	global_load_dwordx4 v[238:241], v177, s[4:5] offset:16 nt
	global_load_dwordx4 v[242:245], v177, s[4:5] offset:512 nt
	global_load_dwordx4 v[246:249], v177, s[4:5] offset:528 nt
	s_waitcnt vmcnt(16)
; DI int grow_of(int lrow, int seg) { return (lrow / SEG) * S + seg * SEG + (lrow % SEG); }
;     DI void operator()(const f32x4 (&acc)[2][2][4][2], const Unit& u, int wr, int wc, int fr, int fq) const {
;         const int b = u.pm / TPB;
;         const int lrow0 = u.pm * BM + wr * 64 + fr;
;         const int col0 = u.pn * BM + wc * 32 + 8 * fq;
;         f32x4 gv[2][2];
; #pragma unroll
;         for (int bj = 0; bj < 2; ++bj)
; #pragma unroll
;             for (int n = 0; n < 2; ++n) gv[bj][n] = *(const f32x4*)(gate + b * 3072 + col0 + bj * HALF + 4 * n);
; #pragma unroll
;         for (int ai = 0; ai < 2; ++ai)
; #pragma unroll
;             for (int m = 0; m < 4; ++m) {
;                 const size_t off = (size_t)grow_of(lrow0 + ai * HALF + m * 16, seg) * D + col0;
; #pragma unroll
;                 for (int bj = 0; bj < 2; ++bj)
; #pragma unroll
;                     for (int n = 0; n < 2; ++n) {
;                         const f32x4 xo = *(const f32x4*)(xin + off + bj * HALF + 4 * n);
;                         *(f32x4*)(xout + off + bj * HALF + 4 * n) = xo + gv[bj][n] * acc[ai][bj][m][n];
;                     }
;             }
;     }
	v_pk_fma_f32 v[180:181], v[82:83], v[142:143], v[180:181]
	v_pk_fma_f32 v[182:183], v[84:85], v[144:145], v[182:183]
	v_pk_fma_f32 v[184:185], v[78:79], v[138:139], v[184:185]
	v_pk_fma_f32 v[186:187], v[80:81], v[140:141], v[186:187]
	v_pk_fma_f32 v[188:189], v[70:71], v[134:135], v[188:189]
	v_pk_fma_f32 v[190:191], v[72:73], v[136:137], v[190:191]
	v_pk_fma_f32 v[192:193], v[66:67], v[130:131], v[192:193]
	v_pk_fma_f32 v[194:195], v[68:69], v[132:133], v[194:195]
	global_store_dwordx4 v175, v[180:183], s[74:75]
	global_store_dwordx4 v175, v[184:187], s[74:75] offset:16
	global_store_dwordx4 v175, v[188:191], s[74:75] offset:512
	global_store_dwordx4 v175, v[192:195], s[74:75] offset:528
	s_nop 1
	global_load_dwordx4 v[180:183], v178, s[4:5] nt
	global_load_dwordx4 v[184:187], v178, s[4:5] offset:16 nt
	global_load_dwordx4 v[188:191], v178, s[4:5] offset:512 nt
	global_load_dwordx4 v[192:195], v178, s[4:5] offset:528 nt
	s_waitcnt vmcnt(16)
	v_pk_fma_f32 v[218:219], v[62:63], v[142:143], v[218:219]
	v_pk_fma_f32 v[220:221], v[64:65], v[144:145], v[220:221]
	v_pk_fma_f32 v[222:223], v[58:59], v[138:139], v[222:223]
	v_pk_fma_f32 v[224:225], v[60:61], v[140:141], v[224:225]
	v_pk_fma_f32 v[226:227], v[54:55], v[134:135], v[226:227]
	v_pk_fma_f32 v[228:229], v[56:57], v[136:137], v[228:229]
	v_pk_fma_f32 v[230:231], v[42:43], v[130:131], v[230:231]
	v_pk_fma_f32 v[232:233], v[44:45], v[132:133], v[232:233]
	global_store_dwordx4 v176, v[218:221], s[74:75]
	global_store_dwordx4 v176, v[222:225], s[74:75] offset:16
	global_store_dwordx4 v176, v[226:229], s[74:75] offset:512
	global_store_dwordx4 v176, v[230:233], s[74:75] offset:528
	s_nop 1
	global_load_dwordx4 v[218:221], v179, s[4:5] nt
	global_load_dwordx4 v[222:225], v179, s[4:5] offset:16 nt
	global_load_dwordx4 v[226:229], v179, s[4:5] offset:512 nt
	global_load_dwordx4 v[230:233], v179, s[4:5] offset:528 nt
	s_waitcnt vmcnt(16)
	v_pk_fma_f32 v[234:235], v[50:51], v[142:143], v[234:235]
	v_pk_fma_f32 v[236:237], v[52:53], v[144:145], v[236:237]
	v_pk_fma_f32 v[238:239], v[46:47], v[138:139], v[238:239]
	v_pk_fma_f32 v[240:241], v[48:49], v[140:141], v[240:241]
	v_pk_fma_f32 v[242:243], v[38:39], v[134:135], v[242:243]
	v_pk_fma_f32 v[244:245], v[40:41], v[136:137], v[244:245]
	v_pk_fma_f32 v[246:247], v[26:27], v[130:131], v[246:247]
	v_pk_fma_f32 v[248:249], v[28:29], v[132:133], v[248:249]
	global_store_dwordx4 v177, v[234:237], s[74:75]
	global_store_dwordx4 v177, v[238:241], s[74:75] offset:16
	global_store_dwordx4 v177, v[242:245], s[74:75] offset:512
	global_store_dwordx4 v177, v[246:249], s[74:75] offset:528
	s_waitcnt vmcnt(12)
	v_pk_fma_f32 v[180:181], v[34:35], v[142:143], v[180:181]
	v_pk_fma_f32 v[182:183], v[36:37], v[144:145], v[182:183]
	v_pk_fma_f32 v[184:185], v[30:31], v[138:139], v[184:185]
	v_pk_fma_f32 v[186:187], v[32:33], v[140:141], v[186:187]
	v_pk_fma_f32 v[188:189], v[22:23], v[134:135], v[188:189]
	v_pk_fma_f32 v[190:191], v[24:25], v[136:137], v[190:191]
	v_pk_fma_f32 v[192:193], v[10:11], v[130:131], v[192:193]
	v_pk_fma_f32 v[194:195], v[12:13], v[132:133], v[194:195]
	global_store_dwordx4 v178, v[180:183], s[74:75]
	global_store_dwordx4 v178, v[184:187], s[74:75] offset:16
	global_store_dwordx4 v178, v[188:191], s[74:75] offset:512
	global_store_dwordx4 v178, v[192:195], s[74:75] offset:528
	s_waitcnt vmcnt(8)
	v_pk_fma_f32 v[218:219], v[18:19], v[142:143], v[218:219]
	v_pk_fma_f32 v[220:221], v[20:21], v[144:145], v[220:221]
	v_pk_fma_f32 v[222:223], v[14:15], v[138:139], v[222:223]
	v_pk_fma_f32 v[224:225], v[16:17], v[140:141], v[224:225]
	v_pk_fma_f32 v[226:227], v[6:7], v[134:135], v[226:227]
	v_pk_fma_f32 v[228:229], v[8:9], v[136:137], v[228:229]
	v_pk_fma_f32 v[230:231], v[2:3], v[130:131], v[230:231]
	v_pk_fma_f32 v[232:233], v[4:5], v[132:133], v[232:233]
	global_store_dwordx4 v179, v[218:221], s[74:75]
	global_store_dwordx4 v179, v[222:225], s[74:75] offset:16
	global_store_dwordx4 v179, v[226:229], s[74:75] offset:512
	global_store_dwordx4 v179, v[230:233], s[74:75] offset:528
	s_cbranch_vccnz .LBB0_781
	s_andn2_b64 vcc, exec, s[0:1]
	s_cbranch_vccnz .LBB0_780
	s_barrier
	s_branch .LBB0_780
